# P6: sample-row tail spread over all 256 workgroups (waves 0-1 of each) instead of all 8 waves of 64 workgroups
# speedup vs baseline: 1.0081x; 1.0009x over previous
; __global__ void __launch_bounds__(512, 2) mega_fwd(Args a) {
;     ...
;         for (int sr = ((bx + 128) % G) * 8 + wid; sr < MS; sr += G * 8) { const int b16 = 8 + (sr >> 6); f32x4 v[4];
;             norm_load(x_s + (size_t)sr * DM, v, lane);
;             sample_combine(MOD + (size_t)b16 * 6144 + 2048, PART, 4, sr, v, lane);
;             row_store_bf16(X1B + (size_t)(MP + sr) * DM, v, lane);
;             row_load_bf16(X1B + (size_t)(MP + sr) * DM, v, lane);
;             norm_apply(v, norm2_g, MOD + (size_t)b16 * 6144 + 4096, MOD + (size_t)b16 * 6144 + 3072, Hb + (size_t)(MP + sr) * DM, lane);
;         } }
.LBB0_1105:
	s_abs_i32 s0, s34
	v_cvt_f32_u32_e32 v1, s0
	s_sub_i32 s9, 0, s0
	s_add_i32 s1, s2, 0x80
	s_ashr_i32 s8, s1, 31
	v_rcp_iflag_f32_e32 v1, v1
	s_abs_i32 s1, s1
	v_mul_f32_e32 v1, 0x4f7ffffe, v1
	v_cvt_u32_f32_e32 v1, v1
	s_nop 0
	v_readfirstlane_b32 s10, v1
	s_mul_i32 s9, s9, s10
	s_mul_hi_u32 s9, s10, s9
	s_add_i32 s10, s10, s9
	s_mul_hi_u32 s9, s1, s10
	s_mul_i32 s9, s9, s0
	s_sub_i32 s1, s1, s9
	s_sub_i32 s9, s1, s0
	s_cmp_ge_u32 s1, s0
	s_cselect_b32 s1, s9, s1
	s_sub_i32 s9, s1, s0
	s_cmp_ge_u32 s1, s0
	s_cselect_b32 s0, s9, s1
	s_xor_b32 s0, s0, s8
	s_sub_i32 s0, s0, s8
	s_lshl_b32 s9, s7, 8
	s_add_i32 s0, s0, s9
	s_cmpk_gt_i32 s0, 0x1ff
	s_cbranch_scc1 .LBB0_1108
	v_readlane_b32 s8, v238, 20
	v_readlane_b32 s10, v238, 22
	v_readlane_b32 s11, v238, 23
	s_ashr_i32 s1, s0, 31
	s_lshl_b64 s[10:11], s[0:1], 12
	v_mov_b32_e32 v11, 0
	v_readlane_b32 s9, v238, 21
	s_add_u32 s8, s30, s10
	v_readlane_b32 s36, v238, 4
	v_or_b32_e32 v16, 0xc0, v4
	v_mov_b32_e32 v1, v11
	v_readlane_b32 s12, v238, 24
	v_readlane_b32 s13, v238, 25
	v_readlane_b32 s14, v238, 26
	v_readlane_b32 s15, v238, 27
	v_readlane_b32 s18, v238, 30
	v_readlane_b32 s19, v238, 31
	s_addc_u32 s9, s31, s11
	s_ashr_i32 s89, s88, 31
	v_readlane_b32 s38, v238, 6
	v_readlane_b32 s39, v238, 7
	v_readlane_b32 s16, v238, 28
	v_readlane_b32 s17, v238, 29
	v_lshl_add_u64 v[8:9], s[18:19], 0, v[0:1]
	v_readlane_b32 s18, v238, 57
	s_lshl_b64 s[12:13], s[88:89], 12
	s_mov_b64 s[14:15], s[38:39]
	v_lshlrev_b32_e32 v15, 4, v16
	v_mbcnt_hi_u32_b32 v16, -1, v207
	v_or_b32_e32 v14, 0x80, v4
	v_readlane_b32 s21, v238, 33
	v_readlane_b32 s22, v238, 34
	v_readlane_b32 s23, v238, 35
	v_readlane_b32 s16, v238, 55
	v_readlane_b32 s19, v238, 58
	s_add_u32 s14, s14, s10
	v_lshlrev_b32_e32 v12, 4, v4
	v_and_b32_e32 v4, 64, v16
	v_lshl_add_u64 v[2:3], s[4:5], 0, v[10:11]
	v_readlane_b32 s17, v238, 56
	v_lshl_add_u64 v[10:11], s[18:19], 0, v[10:11]
	s_addc_u32 s15, s15, s11
	s_mov_b32 s1, 0x1aa00000
	s_mov_b32 s7, 0x1ac00000
	s_mov_b32 s21, 0x1ae00000
	s_mov_b32 s22, 0x1b000000
	v_lshlrev_b32_e32 v13, 4, v6
	v_lshlrev_b32_e32 v14, 4, v14
	v_add_u32_e32 v17, 64, v4
	v_xor_b32_e32 v18, 1, v16
	v_xor_b32_e32 v19, 2, v16
	v_xor_b32_e32 v20, 4, v16
	v_xor_b32_e32 v21, 8, v16
	v_xor_b32_e32 v22, 16, v16
	v_xor_b32_e32 v23, 32, v16
	v_mov_b32_e32 v24, 0x358637bd
	s_mov_b32 s23, 0x800000
	v_readlane_b32 s20, v238, 32
	v_readlane_b32 s37, v238, 5
	v_readlane_b32 s40, v238, 8
	v_readlane_b32 s41, v238, 9
	v_readlane_b32 s42, v238, 10
	v_readlane_b32 s43, v238, 11
	v_readlane_b32 s44, v238, 12
	v_readlane_b32 s45, v238, 13
	v_readlane_b32 s46, v238, 14
	v_readlane_b32 s47, v238, 15
	v_readlane_b32 s48, v238, 16
	v_readlane_b32 s49, v238, 17
	v_readlane_b32 s50, v238, 18
	v_readlane_b32 s51, v238, 19
